# stack j + gqa score tiles fetch K fragments two steps ahead through three register buffers
# speedup vs baseline: 1.0027x; 1.0027x over previous
; __device__ __forceinline__ void finishSM(f32x16& p0, f32x16& p1, float alpha, float& l_reg, bf16x8& pa0, bf16x8& pa1, bf16x8& pa2, bf16x8& pa3) {
; #pragma unroll
;     for (int r = 0; r < 16; ++r) p1[r] = __builtin_amdgcn_exp2f(p1[r]);
;     float ps = 0;
; #pragma unroll
;     for (int r = 0; r < 16; ++r) ps += p0[r];
; #pragma unroll
;     for (int r = 0; r < 16; ++r) ps += p1[r];
;     { auto rr = __builtin_amdgcn_permlane32_swap(__float_as_uint(ps), __float_as_uint(ps), false, false);
;       ps = __uint_as_float(rr[0]) + __uint_as_float(rr[1]); }
;     l_reg = l_reg * alpha + ps;
;     ...
;     PK4(p0, 0, pa0); PK4(p0, 8, pa1); PK4(p1, 0, pa2); PK4(p1, 8, pa3);
;     ...
; }
; template <int DQK> __device__ __forceinline__ void qkt(f32x16& p0, f32x16& p1, const char* Ks, const bf16x8* qr, int r32, int hi) {
;     p0 = f32x16{}; p1 = f32x16{};
; #pragma unroll
;     for (int d0 = 0; d0 < DQK / 16; ++d0) { const int cb = (d0 * 16 + hi * 8) * 2;
;         const bf16x8 b0 = *reinterpret_cast<const bf16x8*>(Ks + kswz<DQK>(r32, cb));
;         const bf16x8 b1 = *reinterpret_cast<const bf16x8*>(Ks + kswz<DQK>(32 + r32, cb));
;         p0 = __builtin_amdgcn_mfma_f32_32x32x16_bf16(b0, qr[d0], p0, 0, 0, 0);
;         p1 = __builtin_amdgcn_mfma_f32_32x32x16_bf16(b1, qr[d0], p1, 0, 0, 0); }
; }
.LBB0_3449:
	s_mov_b32 s24, s25
	s_lshl_b32 s25, s7, 14
	s_add_i32 s14, s25, 0
	v_add_u32_e32 v68, s14, v169
	ds_read_b128 v[64:67], v68 offset:49152
	ds_read_b128 v[68:71], v68 offset:57344
	v_add_u32_e32 v158, s14, v171
	ds_read_b128 v[220:223], v158 offset:49152
	ds_read_b128 v[228:231], v158 offset:57344
	v_add_u32_e32 v158, s14, v170
	ds_read_b128 v[236:239], v158 offset:49152
	ds_read_b128 v[240:243], v158 offset:57344
	v_add_u32_e32 v158, s14, v168
	ds_read_b128 v[244:247], v158 offset:49152
	ds_read_b128 v[232:235], v158 offset:57344
	s_waitcnt lgkmcnt(6)
	v_mfma_f32_32x32x16_bf16 v[80:95], v[64:67], v[124:127], 0
	v_exp_f32_e32 v152, v152
	v_exp_f32_e32 v153, v153
	v_exp_f32_e32 v150, v150
	v_exp_f32_e32 v151, v151
	v_exp_f32_e32 v148, v148
	v_exp_f32_e32 v149, v149
	v_exp_f32_e32 v194, v147
	v_mfma_f32_32x32x16_bf16 v[64:79], v[68:71], v[124:127], 0
	v_exp_f32_e32 v195, v144
	v_exp_f32_e32 v227, v129
	v_cvt_pk_bf16_f32 v129, v207, v210
	v_cvt_pk_bf16_f32 v144, v196, v198
	v_cvt_pk_bf16_f32 v147, v150, v151
	s_waitcnt lgkmcnt(4)
	v_mfma_f32_32x32x16_bf16 v[80:95], v[220:223], v[120:123], v[80:95]
	v_mfma_f32_32x32x16_bf16 v[64:79], v[228:231], v[120:123], v[64:79]
	v_add_u32_e32 v158, s14, v167
	ds_read_b128 v[220:223], v158 offset:49152
	ds_read_b128 v[228:231], v158 offset:57344
	s_waitcnt lgkmcnt(4)
	v_mfma_f32_32x32x16_bf16 v[80:95], v[236:239], v[116:119], v[80:95]
	v_mfma_f32_32x32x16_bf16 v[64:79], v[240:243], v[116:119], v[64:79]
	v_add_u32_e32 v158, s14, v163
	ds_read_b128 v[236:239], v158 offset:49152
	ds_read_b128 v[240:243], v158 offset:57344
	s_waitcnt lgkmcnt(4)
	v_mfma_f32_32x32x16_bf16 v[80:95], v[244:247], v[112:115], v[80:95]
	v_mfma_f32_32x32x16_bf16 v[64:79], v[232:235], v[112:115], v[64:79]
	v_add_u32_e32 v158, s14, v164
	ds_read_b128 v[244:247], v158 offset:49152
	ds_read_b128 v[232:235], v158 offset:57344
	s_waitcnt lgkmcnt(4)
	v_mfma_f32_32x32x16_bf16 v[80:95], v[220:223], v[108:111], v[80:95]
	v_mfma_f32_32x32x16_bf16 v[64:79], v[228:231], v[108:111], v[64:79]
	v_add_u32_e32 v158, s14, v165
	ds_read_b128 v[220:223], v158 offset:49152
	ds_read_b128 v[228:231], v158 offset:57344
	s_waitcnt lgkmcnt(4)
	v_mfma_f32_32x32x16_bf16 v[80:95], v[236:239], v[104:107], v[80:95]
	v_mfma_f32_32x32x16_bf16 v[64:79], v[240:243], v[104:107], v[64:79]
	s_waitcnt lgkmcnt(2)
	v_mfma_f32_32x32x16_bf16 v[80:95], v[244:247], v[100:103], v[80:95]
	v_mfma_f32_32x32x16_bf16 v[64:79], v[232:235], v[100:103], v[64:79]
	v_exp_f32_e32 v158, v146
	v_cvt_pk_bf16_f32 v146, v152, v153
	s_waitcnt lgkmcnt(0)
	v_mfma_f32_32x32x16_bf16 v[80:95], v[220:223], v[96:99], v[80:95]
	v_exp_f32_e32 v223, v128
	v_add_f32_e32 v128, 0, v206
	v_add_f32_e32 v128, v209, v128
	v_add_f32_e32 v128, v207, v128
	v_add_f32_e32 v128, v210, v128
	v_add_f32_e32 v128, v208, v128
	v_add_f32_e32 v128, v211, v128
	v_add_f32_e32 v128, v204, v128
	v_add_f32_e32 v128, v205, v128
	v_add_f32_e32 v128, v200, v128
	v_add_f32_e32 v128, v202, v128
	v_add_f32_e32 v128, v201, v128
	v_add_f32_e32 v128, v203, v128
	v_add_f32_e32 v128, v196, v128
	v_add_f32_e32 v128, v198, v128
	v_add_f32_e32 v128, v197, v128
	v_add_f32_e32 v128, v199, v128
	v_add_f32_e32 v128, v152, v128
	v_add_f32_e32 v128, v153, v128
	v_add_f32_e32 v128, v150, v128
	v_add_f32_e32 v128, v151, v128
	v_add_f32_e32 v128, v148, v128
	v_exp_f32_e32 v220, v145
	v_add_f32_e32 v128, v149, v128
	v_exp_f32_e32 v221, v130
	v_add_f32_e32 v128, v158, v128
	v_exp_f32_e32 v222, v131
	v_add_f32_e32 v128, v194, v128
	v_add_f32_e32 v128, v195, v128
	v_add_f32_e32 v128, v220, v128
	v_mfma_f32_32x32x16_bf16 v[64:79], v[228:231], v[96:99], v[64:79]
	v_exp_f32_e32 v228, v142
	v_add_f32_e32 v128, v221, v128
	v_exp_f32_e32 v229, v143
	v_add_f32_e32 v128, v222, v128
	v_add_f32_e32 v128, v223, v128
	v_add_f32_e32 v128, v227, v128
	v_add_f32_e32 v128, v228, v128
	v_add_f32_e32 v174, v229, v128
	v_mov_b32_e32 v175, v174
	v_cvt_pk_bf16_f32 v128, v206, v209
	v_cvt_pk_bf16_f32 v130, v208, v211
	s_nop 1
	v_permlane32_swap_b32_e32 v174, v175
	v_cvt_pk_bf16_f32 v131, v204, v205
	v_permlane32_swap_b32_e32 v128, v130
	v_cvt_pk_bf16_f32 v142, v200, v202
	v_cvt_pk_bf16_f32 v143, v201, v203
	v_cvt_pk_bf16_f32 v145, v197, v199
	v_cvt_pk_bf16_f32 v148, v148, v149
	v_cvt_pk_bf16_f32 v149, v158, v194
	v_cvt_pk_bf16_f32 v150, v195, v220
	v_cvt_pk_bf16_f32 v151, v221, v222
	v_cvt_pk_bf16_f32 v152, v223, v227
	v_cvt_pk_bf16_f32 v153, v228, v229
	v_permlane32_swap_b32_e32 v129, v131
	v_permlane32_swap_b32_e32 v142, v144
	v_permlane32_swap_b32_e32 v143, v145
	v_permlane32_swap_b32_e32 v146, v148
	v_permlane32_swap_b32_e32 v147, v149
	v_permlane32_swap_b32_e32 v150, v152
	v_permlane32_swap_b32_e32 v151, v153
	s_lshl_b32 s26, s44, 14
	v_add_u32_e32 v158, s26, v159
	ds_read_b64_tr_b16 v[194:195], v158 offset:0
	ds_read_b64_tr_b16 v[196:197], v158 offset:0x800
	ds_read_b64_tr_b16 v[198:199], v158 offset:0x1000
	ds_read_b64_tr_b16 v[200:201], v158 offset:0x1800
	ds_read_b64_tr_b16 v[202:203], v158 offset:0x2000
	ds_read_b64_tr_b16 v[204:205], v158 offset:0x2800
	ds_read_b64_tr_b16 v[206:207], v158 offset:0x3000
	ds_read_b64_tr_b16 v[208:209], v158 offset:0x3800
	s_waitcnt lgkmcnt(0)
; #define SBAR() __builtin_amdgcn_sched_barrier(0)
; template <int D0> __device__ __forceinline__ void pv_one(f32x16& od, int vb, bf16x8 pa0, bf16x8 pa1, bf16x8 pa2, bf16x8 pa3) {
;     const s16x4 l0 = tr_read<v_rd_off(D0, 0, 0)>(vb), h0 = tr_read<v_rd_off(D0, 0, 1)>(vb), l1 = tr_read<v_rd_off(D0, 1, 0)>(vb), h1 = tr_read<v_rd_off(D0, 1, 1)>(vb);
;     const s16x4 l2 = tr_read<v_rd_off(D0, 2, 0)>(vb), h2 = tr_read<v_rd_off(D0, 2, 1)>(vb), l3 = tr_read<v_rd_off(D0, 3, 0)>(vb), h3 = tr_read<v_rd_off(D0, 3, 1)>(vb);
;     asm volatile("s_waitcnt lgkmcnt(0)" ::: "memory"); SBAR();
;     ...
;     od = __builtin_amdgcn_mfma_f32_32x32x16_bf16(pa0, PK(l0, h0), od, 0, 0, 0);
;     od = __builtin_amdgcn_mfma_f32_32x32x16_bf16(pa1, PK(l1, h1), od, 0, 0, 0);
;     od = __builtin_amdgcn_mfma_f32_32x32x16_bf16(pa2, PK(l2, h2), od, 0, 0, 0);
;     od = __builtin_amdgcn_mfma_f32_32x32x16_bf16(pa3, PK(l3, h3), od, 0, 0, 0);
;     ...
; }
; __device__ __forceinline__ void pv_d0(f32x16* o, int vb, bf16x8 pa0, bf16x8 pa1, bf16x8 pa2, bf16x8 pa3) {
;     pv_one<0>(o[0], vb, pa0, pa1, pa2, pa3); pv_one<1>(o[1], vb, pa0, pa1, pa2, pa3); pv_one<2>(o[2], vb, pa0, pa1, pa2, pa3); pv_one<3>(o[3], vb, pa0, pa1, pa2, pa3);
; }
; __device__ __forceinline__ void partialSM(f32x16& p0, f32x16& p1, float& m_reg, float& mn, float& alpha, const float C, const float thr_raw) {
;     float pmax = p0[0];
; #pragma unroll
;     for (int r = 1; r < 16; ++r) pmax = fmaxf(pmax, p0[r]);
; #pragma unroll
;     for (int r = 0; r < 16; ++r) pmax = fmaxf(pmax, p1[r]);
;     { auto rr = __builtin_amdgcn_permlane32_swap(__float_as_uint(pmax), __float_as_uint(pmax), false, false);
;       pmax = fmaxf(__uint_as_float(rr[0]), __uint_as_float(rr[1])); }
;     if (__builtin_expect(__all(pmax - m_reg <= thr_raw), 1)) { mn = m_reg; alpha = 1.f; }
;     else { mn = fmaxf(m_reg, pmax); alpha = __builtin_amdgcn_exp2f((m_reg - mn) * C); m_reg = mn; }
	s_nop 0
	v_mfma_f32_32x32x16_bf16 v[0:15], v[128:131], v[194:197], v[0:15]
	ds_read_b64_tr_b16 v[194:195], v158 offset:0x200
	ds_read_b64_tr_b16 v[196:197], v158 offset:0xa00
	v_mfma_f32_32x32x16_bf16 v[0:15], v[142:145], v[198:201], v[0:15]
	ds_read_b64_tr_b16 v[198:199], v158 offset:0x1200
	ds_read_b64_tr_b16 v[200:201], v158 offset:0x1a00
	v_mfma_f32_32x32x16_bf16 v[0:15], v[146:149], v[202:205], v[0:15]
	ds_read_b64_tr_b16 v[202:203], v158 offset:0x2200
	ds_read_b64_tr_b16 v[204:205], v158 offset:0x2a00
	v_mfma_f32_32x32x16_bf16 v[0:15], v[150:153], v[206:209], v[0:15]
	ds_read_b64_tr_b16 v[206:207], v158 offset:0x3200
	ds_read_b64_tr_b16 v[208:209], v158 offset:0x3a00
	s_waitcnt lgkmcnt(0)
	v_mfma_f32_32x32x16_bf16 v[48:63], v[128:131], v[194:197], v[48:63]
	ds_read_b64_tr_b16 v[194:195], v158 offset:0x400
	ds_read_b64_tr_b16 v[196:197], v158 offset:0xc00
	v_mfma_f32_32x32x16_bf16 v[48:63], v[142:145], v[198:201], v[48:63]
	ds_read_b64_tr_b16 v[198:199], v158 offset:0x1400
	ds_read_b64_tr_b16 v[200:201], v158 offset:0x1c00
	v_mfma_f32_32x32x16_bf16 v[48:63], v[146:149], v[202:205], v[48:63]
	ds_read_b64_tr_b16 v[202:203], v158 offset:0x2400
	ds_read_b64_tr_b16 v[204:205], v158 offset:0x2c00
	v_mfma_f32_32x32x16_bf16 v[48:63], v[150:153], v[206:209], v[48:63]
	ds_read_b64_tr_b16 v[206:207], v158 offset:0x3400
	ds_read_b64_tr_b16 v[208:209], v158 offset:0x3c00
	s_waitcnt lgkmcnt(0)
	v_mfma_f32_32x32x16_bf16 v[32:47], v[128:131], v[194:197], v[32:47]
	ds_read_b64_tr_b16 v[194:195], v158 offset:0x600
	ds_read_b64_tr_b16 v[196:197], v158 offset:0xe00
	v_mfma_f32_32x32x16_bf16 v[32:47], v[142:145], v[198:201], v[32:47]
	ds_read_b64_tr_b16 v[198:199], v158 offset:0x1600
	ds_read_b64_tr_b16 v[200:201], v158 offset:0x1e00
	v_mfma_f32_32x32x16_bf16 v[32:47], v[146:149], v[202:205], v[32:47]
	ds_read_b64_tr_b16 v[202:203], v158 offset:0x2600
	ds_read_b64_tr_b16 v[204:205], v158 offset:0x2e00
	v_mfma_f32_32x32x16_bf16 v[32:47], v[150:153], v[206:209], v[32:47]
	ds_read_b64_tr_b16 v[206:207], v158 offset:0x3600
	ds_read_b64_tr_b16 v[208:209], v158 offset:0x3e00
	s_waitcnt lgkmcnt(0)
	v_mfma_f32_32x32x16_bf16 v[16:31], v[128:131], v[194:197], v[16:31]
	v_max_f32_e32 v128, v81, v81
	v_max_f32_e32 v129, v80, v80
	v_max_f32_e32 v128, v129, v128
	v_max3_f32 v128, v128, v82, v83
	v_max3_f32 v128, v128, v84, v85
	v_max3_f32 v128, v128, v86, v87
	v_max3_f32 v128, v128, v88, v89
	v_mfma_f32_32x32x16_bf16 v[16:31], v[142:145], v[198:201], v[16:31]
	v_max3_f32 v128, v128, v90, v91
	v_max3_f32 v128, v128, v92, v93
	v_max3_f32 v128, v128, v94, v95
	v_max3_f32 v128, v128, v64, v65
	v_max3_f32 v128, v128, v66, v67
	v_max3_f32 v128, v128, v68, v69
	v_max3_f32 v128, v128, v70, v71
	v_mfma_f32_32x32x16_bf16 v[16:31], v[146:149], v[202:205], v[16:31]
	v_max3_f32 v128, v128, v72, v73
	v_max3_f32 v128, v128, v74, v75
	v_max3_f32 v128, v128, v76, v77
	v_max3_f32 v128, v128, v78, v79
	v_mov_b32_e32 v129, v128
	s_nop 1
	v_permlane32_swap_b32_e32 v128, v129
	v_mfma_f32_32x32x16_bf16 v[16:31], v[150:153], v[206:209], v[16:31]
	v_max_f32_e32 v129, v129, v129
	v_max_f32_e32 v128, v128, v128
	v_max_f32_e32 v128, v128, v129
	v_sub_f32_e32 v129, v128, v172
	v_cmp_ge_f32_e32 vcc, s20, v129
	s_cmp_eq_u64 vcc, exec
	s_waitcnt vmcnt(0)
	s_cselect_b64 s[40:41], -1, 0
	s_add_i32 s14, s22, -1
	v_cmp_lt_u32_e32 vcc, s14, v160
	s_waitcnt vmcnt(0)
	s_barrier
	s_and_saveexec_b64 s[42:43], vcc
	s_cbranch_execz .LBB0_3451
	s_sub_i32 s14, s23, 64
	v_cmp_lt_u32_e32 vcc, s14, v161
	s_nop 1
	v_cndmask_b32_e32 v129, v166, v162, vcc
	v_add_u32_e32 v130, s14, v129
	v_ashrrev_i32_e32 v131, 31, v130
	v_lshlrev_b64 v[130:131], 8, v[130:131]
	v_lshl_add_u64 v[142:143], s[86:87], 0, v[130:131]
	s_add_i32 s14, s6, s26
	v_lshl_add_u64 v[144:145], v[134:135], 1, v[142:143]
	s_mov_b32 m0, s14
	v_lshl_add_u64 v[142:143], v[136:137], 1, v[142:143]
	global_load_lds_dwordx4 v[144:145], off
	s_add_i32 m0, s14, 0x2000
	v_lshl_add_u64 v[130:131], s[84:85], 0, v[130:131]
	global_load_lds_dwordx4 v[142:143], off
	s_add_i32 m0, s14, 0xc000
	v_lshl_add_u64 v[142:143], v[138:139], 1, v[130:131]
	global_load_lds_dwordx4 v[142:143], off
	v_lshl_add_u64 v[130:131], v[140:141], 1, v[130:131]
	s_add_i32 m0, s14, 0xe000
	s_nop 0
	global_load_lds_dwordx4 v[130:131], off

; __device__ __forceinline__ void partialSM(f32x16& p0, f32x16& p1, float& m_reg, float& mn, float& alpha, const float C, const float thr_raw) {
;     ...
;     const float mnC = -mn * C;
; #pragma unroll
;     for (int r = 0; r < 16; ++r) p0[r] = fmaf(p0[r], C, mnC);
; #pragma unroll
;     for (int r = 0; r < 16; ++r) p1[r] = fmaf(p1[r], C, mnC);
; #pragma unroll
;     for (int r = 0; r < 16; ++r) p0[r] = __builtin_amdgcn_exp2f(p0[r]);
; }
; __device__ __forceinline__ void finishSM(f32x16& p0, f32x16& p1, float alpha, float& l_reg, bf16x8& pa0, bf16x8& pa1, bf16x8& pa2, bf16x8& pa3) {
; #pragma unroll
;     for (int r = 0; r < 16; ++r) p1[r] = __builtin_amdgcn_exp2f(p1[r]);
;     float ps = 0;
; #pragma unroll
;     for (int r = 0; r < 16; ++r) ps += p0[r];
; #pragma unroll
;     for (int r = 0; r < 16; ++r) ps += p1[r];
;     { auto rr = __builtin_amdgcn_permlane32_swap(__float_as_uint(ps), __float_as_uint(ps), false, false);
;       ps = __uint_as_float(rr[0]) + __uint_as_float(rr[1]); }
;     l_reg = l_reg * alpha + ps;
;     ...
;     PK4(p0, 0, pa0); PK4(p0, 8, pa1); PK4(p1, 0, pa2); PK4(p1, 8, pa3);
;     ...
; }
; template <int DQK> __device__ __forceinline__ void qkt(f32x16& p0, f32x16& p1, const char* Ks, const bf16x8* qr, int r32, int hi) {
;     p0 = f32x16{}; p1 = f32x16{};
; #pragma unroll
;     for (int d0 = 0; d0 < DQK / 16; ++d0) { const int cb = (d0 * 16 + hi * 8) * 2;
;         const bf16x8 b0 = *reinterpret_cast<const bf16x8*>(Ks + kswz<DQK>(r32, cb));
;         const bf16x8 b1 = *reinterpret_cast<const bf16x8*>(Ks + kswz<DQK>(32 + r32, cb));
;         p0 = __builtin_amdgcn_mfma_f32_32x32x16_bf16(b0, qr[d0], p0, 0, 0, 0);
;         p1 = __builtin_amdgcn_mfma_f32_32x32x16_bf16(b1, qr[d0], p1, 0, 0, 0); }
; }
.LBB0_3455:
	v_cndmask_b32_e64 v142, v128, v172, s[40:41]
	v_mul_f32_e32 v194, 0xbe0293ee, v142
	v_fmamk_f32 v80, v80, 0x3e0293ee, v194
	v_exp_f32_e32 v128, v80
	v_fmamk_f32 v81, v81, 0x3e0293ee, v194
	v_fmamk_f32 v82, v82, 0x3e0293ee, v194
	v_fmamk_f32 v83, v83, 0x3e0293ee, v194
	v_fmamk_f32 v84, v84, 0x3e0293ee, v194
	v_fmamk_f32 v85, v85, 0x3e0293ee, v194
	v_fmamk_f32 v86, v86, 0x3e0293ee, v194
	v_fmamk_f32 v87, v87, 0x3e0293ee, v194
	v_fmamk_f32 v88, v88, 0x3e0293ee, v194
	v_fmamk_f32 v89, v89, 0x3e0293ee, v194
	v_fmamk_f32 v90, v90, 0x3e0293ee, v194
	v_fmamk_f32 v91, v91, 0x3e0293ee, v194
	v_fmamk_f32 v92, v92, 0x3e0293ee, v194
	v_fmamk_f32 v93, v93, 0x3e0293ee, v194
	v_fmamk_f32 v94, v94, 0x3e0293ee, v194
	v_fmamk_f32 v95, v95, 0x3e0293ee, v194
	v_fmamk_f32 v204, v64, 0x3e0293ee, v194
	v_fmamk_f32 v205, v65, 0x3e0293ee, v194
	v_fmamk_f32 v206, v66, 0x3e0293ee, v194
	v_fmamk_f32 v207, v67, 0x3e0293ee, v194
	v_fmamk_f32 v208, v68, 0x3e0293ee, v194
	v_fmamk_f32 v197, v69, 0x3e0293ee, v194
	v_fmamk_f32 v198, v70, 0x3e0293ee, v194
	v_fmamk_f32 v199, v71, 0x3e0293ee, v194
	v_fmamk_f32 v200, v72, 0x3e0293ee, v194
	v_fmamk_f32 v201, v73, 0x3e0293ee, v194
	v_fmamk_f32 v202, v74, 0x3e0293ee, v194
	v_fmamk_f32 v203, v75, 0x3e0293ee, v194
	v_fmamk_f32 v196, v76, 0x3e0293ee, v194
	v_exp_f32_e32 v172, v81
	v_exp_f32_e32 v129, v82
	v_exp_f32_e32 v153, v83
	v_exp_f32_e32 v130, v84
	v_exp_f32_e32 v152, v85
	v_exp_f32_e32 v131, v86
	v_exp_f32_e32 v151, v87
	v_exp_f32_e32 v148, v88
	v_exp_f32_e32 v150, v89
	v_exp_f32_e32 v147, v90
	v_exp_f32_e32 v149, v91
	v_exp_f32_e32 v144, v92
	v_exp_f32_e32 v146, v93
	v_exp_f32_e32 v143, v94
	v_exp_f32_e32 v145, v95
	v_fmamk_f32 v209, v77, 0x3e0293ee, v194
	v_fmamk_f32 v210, v78, 0x3e0293ee, v194
	v_fmac_f32_e32 v194, 0x3e0293ee, v79
	s_lshl_b32 s27, s24, 14
	s_add_i32 s14, s27, 0
	v_add_u32_e32 v68, s14, v169
	ds_read_b128 v[64:67], v68 offset:49152
	ds_read_b128 v[68:71], v68 offset:57344
	v_add_u32_e32 v211, s14, v171
	ds_read_b128 v[220:223], v211 offset:49152
	ds_read_b128 v[228:231], v211 offset:57344
	v_add_u32_e32 v211, s14, v170
	ds_read_b128 v[236:239], v211 offset:49152
	ds_read_b128 v[240:243], v211 offset:57344
	v_add_u32_e32 v211, s14, v168
	ds_read_b128 v[244:247], v211 offset:49152
	ds_read_b128 v[232:235], v211 offset:57344
	s_waitcnt lgkmcnt(6)
	v_mfma_f32_32x32x16_bf16 v[80:95], v[64:67], v[124:127], 0
	v_exp_f32_e32 v204, v204
	v_exp_f32_e32 v205, v205
	v_exp_f32_e32 v206, v206
	v_exp_f32_e32 v207, v207
	v_exp_f32_e32 v208, v208
	v_exp_f32_e32 v197, v197
	v_exp_f32_e32 v198, v198
	v_mfma_f32_32x32x16_bf16 v[64:79], v[68:71], v[124:127], 0
	v_exp_f32_e32 v199, v199
	v_exp_f32_e32 v200, v200
	v_exp_f32_e32 v201, v201
	v_exp_f32_e32 v202, v202
	v_exp_f32_e32 v203, v203
	v_exp_f32_e32 v209, v209
	v_exp_f32_e32 v210, v210
	s_waitcnt lgkmcnt(4)
	v_mfma_f32_32x32x16_bf16 v[80:95], v[220:223], v[120:123], v[80:95]
	v_exp_f32_e32 v194, v194
	v_mfma_f32_32x32x16_bf16 v[64:79], v[228:231], v[120:123], v[64:79]
	v_add_u32_e32 v211, s14, v167
	ds_read_b128 v[220:223], v211 offset:49152
	ds_read_b128 v[228:231], v211 offset:57344
	s_waitcnt lgkmcnt(4)
	v_mfma_f32_32x32x16_bf16 v[80:95], v[236:239], v[116:119], v[80:95]
	v_mfma_f32_32x32x16_bf16 v[64:79], v[240:243], v[116:119], v[64:79]
	v_add_u32_e32 v211, s14, v163
	ds_read_b128 v[236:239], v211 offset:49152
	ds_read_b128 v[240:243], v211 offset:57344
	s_waitcnt lgkmcnt(4)
	v_mfma_f32_32x32x16_bf16 v[80:95], v[244:247], v[112:115], v[80:95]
	v_mfma_f32_32x32x16_bf16 v[64:79], v[232:235], v[112:115], v[64:79]
	v_add_u32_e32 v211, s14, v164
	ds_read_b128 v[244:247], v211 offset:49152
	ds_read_b128 v[232:235], v211 offset:57344
	s_waitcnt lgkmcnt(4)
	v_mfma_f32_32x32x16_bf16 v[80:95], v[220:223], v[108:111], v[80:95]
	v_mfma_f32_32x32x16_bf16 v[64:79], v[228:231], v[108:111], v[64:79]
	v_add_u32_e32 v211, s14, v165
	ds_read_b128 v[220:223], v211 offset:49152
	ds_read_b128 v[228:231], v211 offset:57344
	s_waitcnt lgkmcnt(4)
	v_mfma_f32_32x32x16_bf16 v[80:95], v[236:239], v[104:107], v[80:95]
	v_mfma_f32_32x32x16_bf16 v[64:79], v[240:243], v[104:107], v[64:79]
	s_waitcnt lgkmcnt(2)
	v_mfma_f32_32x32x16_bf16 v[80:95], v[244:247], v[100:103], v[80:95]
	v_mfma_f32_32x32x16_bf16 v[64:79], v[232:235], v[100:103], v[64:79]
	v_exp_f32_e32 v211, v196
	v_add_f32_e32 v196, 0, v128
	v_add_f32_e32 v196, v172, v196
	v_add_f32_e32 v196, v129, v196
	v_add_f32_e32 v196, v153, v196
	v_add_f32_e32 v196, v130, v196
	v_add_f32_e32 v196, v152, v196
	v_add_f32_e32 v196, v131, v196
	v_add_f32_e32 v196, v151, v196
	v_add_f32_e32 v196, v148, v196
	v_add_f32_e32 v196, v150, v196
	v_add_f32_e32 v196, v147, v196
	v_add_f32_e32 v196, v149, v196
	v_add_f32_e32 v196, v144, v196
	v_add_f32_e32 v196, v146, v196
	v_add_f32_e32 v196, v143, v196
	v_add_f32_e32 v196, v145, v196
	v_add_f32_e32 v196, v204, v196
	v_add_f32_e32 v196, v205, v196
	v_add_f32_e32 v196, v206, v196
	v_add_f32_e32 v196, v207, v196
	v_add_f32_e32 v196, v208, v196
	v_add_f32_e32 v196, v197, v196
	v_add_f32_e32 v196, v198, v196
	v_add_f32_e32 v196, v199, v196
	v_add_f32_e32 v196, v200, v196
	v_add_f32_e32 v196, v201, v196
	s_waitcnt lgkmcnt(0)
; template <int D0> __device__ __forceinline__ void pv_one(f32x16& od, int vb, bf16x8 pa0, bf16x8 pa1, bf16x8 pa2, bf16x8 pa3) {
;     const s16x4 l0 = tr_read<v_rd_off(D0, 0, 0)>(vb), h0 = tr_read<v_rd_off(D0, 0, 1)>(vb), l1 = tr_read<v_rd_off(D0, 1, 0)>(vb), h1 = tr_read<v_rd_off(D0, 1, 1)>(vb);
;     const s16x4 l2 = tr_read<v_rd_off(D0, 2, 0)>(vb), h2 = tr_read<v_rd_off(D0, 2, 1)>(vb), l3 = tr_read<v_rd_off(D0, 3, 0)>(vb), h3 = tr_read<v_rd_off(D0, 3, 1)>(vb);
;     asm volatile("s_waitcnt lgkmcnt(0)" ::: "memory"); SBAR();
;     ...
;     od = __builtin_amdgcn_mfma_f32_32x32x16_bf16(pa0, PK(l0, h0), od, 0, 0, 0);
;     od = __builtin_amdgcn_mfma_f32_32x32x16_bf16(pa1, PK(l1, h1), od, 0, 0, 0);
;     od = __builtin_amdgcn_mfma_f32_32x32x16_bf16(pa2, PK(l2, h2), od, 0, 0, 0);
;     od = __builtin_amdgcn_mfma_f32_32x32x16_bf16(pa3, PK(l3, h3), od, 0, 0, 0);
;     ...
; }
; __device__ __forceinline__ void pv_d0(f32x16* o, int vb, bf16x8 pa0, bf16x8 pa1, bf16x8 pa2, bf16x8 pa3) {
;     pv_one<0>(o[0], vb, pa0, pa1, pa2, pa3); pv_one<1>(o[1], vb, pa0, pa1, pa2, pa3); pv_one<2>(o[2], vb, pa0, pa1, pa2, pa3); pv_one<3>(o[3], vb, pa0, pa1, pa2, pa3);
; }
; __device__ __forceinline__ void partialSM(f32x16& p0, f32x16& p1, float& m_reg, float& mn, float& alpha, const float C, const float thr_raw) {
;     float pmax = p0[0];
; #pragma unroll
;     for (int r = 1; r < 16; ++r) pmax = fmaxf(pmax, p0[r]);
; #pragma unroll
;     for (int r = 0; r < 16; ++r) pmax = fmaxf(pmax, p1[r]);
;     { auto rr = __builtin_amdgcn_permlane32_swap(__float_as_uint(pmax), __float_as_uint(pmax), false, false);
;       pmax = fmaxf(__uint_as_float(rr[0]), __uint_as_float(rr[1])); }
;     if (__builtin_expect(__all(pmax - m_reg <= thr_raw), 1)) { mn = m_reg; alpha = 1.f; }
;     else { mn = fmaxf(m_reg, pmax); alpha = __builtin_amdgcn_exp2f((m_reg - mn) * C); m_reg = mn; }
;     const float mnC = -mn * C;
; #pragma unroll
;     for (int r = 0; r < 16; ++r) p0[r] = fmaf(p0[r], C, mnC);
; #pragma unroll
;     for (int r = 0; r < 16; ++r) p1[r] = fmaf(p1[r], C, mnC);
; #pragma unroll
;     for (int r = 0; r < 16; ++r) p0[r] = __builtin_amdgcn_exp2f(p0[r]);
; }
; __device__ __forceinline__ void finishSM(f32x16& p0, f32x16& p1, float alpha, float& l_reg, bf16x8& pa0, bf16x8& pa1, bf16x8& pa2, bf16x8& pa3) {
; #pragma unroll
;     for (int r = 0; r < 16; ++r) p1[r] = __builtin_amdgcn_exp2f(p1[r]);
	v_mfma_f32_32x32x16_bf16 v[80:95], v[220:223], v[96:99], v[80:95]
	v_add_f32_e32 v196, v202, v196
	v_add_f32_e32 v196, v203, v196
	v_add_f32_e32 v196, v211, v196
	v_add_f32_e32 v196, v209, v196
	v_add_f32_e32 v196, v210, v196
	v_add_f32_e32 v227, v194, v196
	v_cvt_pk_bf16_f32 v128, v128, v172
	v_mfma_f32_32x32x16_bf16 v[64:79], v[228:231], v[96:99], v[64:79]
	v_mov_b32_e32 v228, v227
	v_cvt_pk_bf16_f32 v130, v130, v152
	s_nop 1
	v_permlane32_swap_b32_e32 v227, v228
	v_cvt_pk_bf16_f32 v129, v129, v153
	v_cvt_pk_bf16_f32 v131, v131, v151
	v_permlane32_swap_b32_e32 v128, v130
	v_cvt_pk_bf16_f32 v148, v148, v150
	v_cvt_pk_bf16_f32 v149, v147, v149
	v_cvt_pk_bf16_f32 v150, v144, v146
	v_cvt_pk_bf16_f32 v151, v143, v145
	v_cvt_pk_bf16_f32 v144, v204, v205
	v_cvt_pk_bf16_f32 v145, v206, v207
	v_cvt_pk_bf16_f32 v146, v208, v197
	v_cvt_pk_bf16_f32 v147, v198, v199
	v_cvt_pk_bf16_f32 v196, v200, v201
	v_cvt_pk_bf16_f32 v197, v202, v203
	v_cvt_pk_bf16_f32 v198, v211, v209
	v_cvt_pk_bf16_f32 v199, v210, v194
	v_permlane32_swap_b32_e32 v129, v131
	v_permlane32_swap_b32_e32 v148, v150
	v_permlane32_swap_b32_e32 v149, v151
	v_permlane32_swap_b32_e32 v144, v146
	v_permlane32_swap_b32_e32 v145, v147
	v_permlane32_swap_b32_e32 v196, v198
	v_permlane32_swap_b32_e32 v197, v199
	v_add_u32_e32 v143, s25, v159
	ds_read_b64_tr_b16 v[200:201], v143 offset:0
	ds_read_b64_tr_b16 v[202:203], v143 offset:0x800
	ds_read_b64_tr_b16 v[204:205], v143 offset:0x1000
	ds_read_b64_tr_b16 v[206:207], v143 offset:0x1800
	ds_read_b64_tr_b16 v[208:209], v143 offset:0x2000
	ds_read_b64_tr_b16 v[210:211], v143 offset:0x2800
	ds_read_b64_tr_b16 v[220:221], v143 offset:0x3000
	ds_read_b64_tr_b16 v[222:223], v143 offset:0x3800
	s_waitcnt lgkmcnt(0)
	s_nop 0
	v_mfma_f32_32x32x16_bf16 v[0:15], v[128:131], v[200:203], v[0:15]
	ds_read_b64_tr_b16 v[200:201], v143 offset:0x200
	ds_read_b64_tr_b16 v[202:203], v143 offset:0xa00
	v_mfma_f32_32x32x16_bf16 v[0:15], v[148:151], v[204:207], v[0:15]
	ds_read_b64_tr_b16 v[204:205], v143 offset:0x1200
	ds_read_b64_tr_b16 v[206:207], v143 offset:0x1a00
	v_mfma_f32_32x32x16_bf16 v[0:15], v[144:147], v[208:211], v[0:15]
	ds_read_b64_tr_b16 v[208:209], v143 offset:0x2200
	ds_read_b64_tr_b16 v[210:211], v143 offset:0x2a00
	v_mfma_f32_32x32x16_bf16 v[0:15], v[196:199], v[220:223], v[0:15]
	ds_read_b64_tr_b16 v[220:221], v143 offset:0x3200
	ds_read_b64_tr_b16 v[222:223], v143 offset:0x3a00
	s_waitcnt lgkmcnt(0)
	v_mfma_f32_32x32x16_bf16 v[48:63], v[128:131], v[200:203], v[48:63]
	ds_read_b64_tr_b16 v[200:201], v143 offset:0x400
	ds_read_b64_tr_b16 v[202:203], v143 offset:0xc00
	v_mfma_f32_32x32x16_bf16 v[48:63], v[148:151], v[204:207], v[48:63]
	ds_read_b64_tr_b16 v[204:205], v143 offset:0x1400
	ds_read_b64_tr_b16 v[206:207], v143 offset:0x1c00
	v_mfma_f32_32x32x16_bf16 v[48:63], v[144:147], v[208:211], v[48:63]
	ds_read_b64_tr_b16 v[208:209], v143 offset:0x2400
	ds_read_b64_tr_b16 v[210:211], v143 offset:0x2c00
	v_mfma_f32_32x32x16_bf16 v[48:63], v[196:199], v[220:223], v[48:63]
	ds_read_b64_tr_b16 v[220:221], v143 offset:0x3400
	ds_read_b64_tr_b16 v[222:223], v143 offset:0x3c00
	s_waitcnt lgkmcnt(0)
	v_mfma_f32_32x32x16_bf16 v[32:47], v[128:131], v[200:203], v[32:47]
	ds_read_b64_tr_b16 v[200:201], v143 offset:0x600
	ds_read_b64_tr_b16 v[202:203], v143 offset:0xe00
	v_mfma_f32_32x32x16_bf16 v[32:47], v[148:151], v[204:207], v[32:47]
	ds_read_b64_tr_b16 v[204:205], v143 offset:0x1600
	ds_read_b64_tr_b16 v[206:207], v143 offset:0x1e00
	v_mfma_f32_32x32x16_bf16 v[32:47], v[144:147], v[208:211], v[32:47]
	ds_read_b64_tr_b16 v[208:209], v143 offset:0x2600
	ds_read_b64_tr_b16 v[210:211], v143 offset:0x2e00
	v_mfma_f32_32x32x16_bf16 v[32:47], v[196:199], v[220:223], v[32:47]
	ds_read_b64_tr_b16 v[220:221], v143 offset:0x3600
	ds_read_b64_tr_b16 v[222:223], v143 offset:0x3e00
	s_waitcnt lgkmcnt(0)
	v_mfma_f32_32x32x16_bf16 v[16:31], v[128:131], v[200:203], v[16:31]
	v_max_f32_e32 v128, v81, v81
	v_max_f32_e32 v129, v80, v80
	v_max_f32_e32 v128, v129, v128
	v_max3_f32 v128, v128, v82, v83
	v_max3_f32 v128, v128, v84, v85
	v_max3_f32 v128, v128, v86, v87
	v_max3_f32 v128, v128, v88, v89
	v_mfma_f32_32x32x16_bf16 v[16:31], v[148:151], v[204:207], v[16:31]
	v_max3_f32 v128, v128, v90, v91
	v_max3_f32 v128, v128, v92, v93
	v_max3_f32 v128, v128, v94, v95
	v_max3_f32 v128, v128, v64, v65
	v_max3_f32 v128, v128, v66, v67
	v_max3_f32 v128, v128, v68, v69
	v_max3_f32 v128, v128, v70, v71
	v_mfma_f32_32x32x16_bf16 v[16:31], v[144:147], v[208:211], v[16:31]
	v_max3_f32 v128, v128, v72, v73
	v_max3_f32 v128, v128, v74, v75
	v_max3_f32 v128, v128, v76, v77
	v_max3_f32 v128, v128, v78, v79
	v_mov_b32_e32 v129, v128
	s_nop 1
	v_permlane32_swap_b32_e32 v128, v129
	v_mfma_f32_32x32x16_bf16 v[16:31], v[196:199], v[220:223], v[16:31]
	v_max_f32_e32 v129, v129, v129
	v_max_f32_e32 v128, v128, v128
	v_max_f32_e32 v128, v128, v129
	v_sub_f32_e32 v129, v128, v142
	v_cmp_ge_f32_e32 vcc, s20, v129
	s_waitcnt vmcnt(0)
	s_cmp_eq_u64 vcc, exec
	s_cselect_b64 s[42:43], -1, 0
	v_cmp_lt_u32_e32 vcc, s22, v160
	v_cmp_ge_u32_e64 s[40:41], s22, v160
	s_waitcnt vmcnt(0)
	s_barrier
	s_and_saveexec_b64 s[48:49], vcc
	s_cbranch_execz .LBB0_3457
	v_cmp_lt_u32_e32 vcc, s23, v161
	s_add_i32 s14, s6, s25
	s_mov_b32 m0, s14
	v_cndmask_b32_e32 v129, v166, v162, vcc
	v_add_u32_e32 v130, s23, v129
	v_ashrrev_i32_e32 v131, 31, v130
	v_lshlrev_b64 v[130:131], 8, v[130:131]
	v_lshl_add_u64 v[144:145], s[86:87], 0, v[130:131]
	v_lshl_add_u64 v[146:147], v[134:135], 1, v[144:145]
	global_load_lds_dwordx4 v[146:147], off
	v_lshl_add_u64 v[144:145], v[136:137], 1, v[144:145]
	s_add_i32 m0, s14, 0x2000
	v_lshl_add_u64 v[130:131], s[84:85], 0, v[130:131]
	global_load_lds_dwordx4 v[144:145], off
	s_add_i32 m0, s14, 0xc000
	v_lshl_add_u64 v[144:145], v[138:139], 1, v[130:131]
	global_load_lds_dwordx4 v[144:145], off
	v_lshl_add_u64 v[130:131], v[140:141], 1, v[130:131]
	s_add_i32 m0, s14, 0xe000
	s_nop 0
	global_load_lds_dwordx4 v[130:131], off
